# same as rope-pipeline version plus the 2 wait states the ISA requires between v_add_co (writes VCC) and v_addc (reads VCC) in the new address setup
# baseline (speedup 1.0000x reference)
; __device__ __forceinline__ void mla_up_tile(const Params& p, int b, int it, unsigned char* lds) {
;     ...
;         const int pn = it % 3, pm = it / 3;
;         gemm_big(PB + (size_t)pm * 128 * PBW + PB_CQ, PBW, wb + W_UQ + (size_t)pn * 256 * 256, 256, acc, lds);
;         const float* RQ = (const float*)(p.ws + OFF_RQ);
;         const float* rope = (const float*)(p.ws + OFF_ROPE);
;         bf16_t* QF = (bf16_t*)(p.ws + OFF_QF);
;         const float qsc = 0.10206207261596575f * LOG2E;
; #pragma unroll
;         for (int mi = 0; mi < 2; ++mi)
; #pragma unroll
;             for (int reg = 0; reg < 16; ++reg) {
;                 const int m = pm * 128 + wr * 64 + mi * 32 + (reg & 3) + 8 * (reg >> 2) + 4 * h;
;                 const float rq = RQ[m] ;
;                 const float* rp = rope + (size_t)(b * TH + m) * 32;
;                 const float cs = rp[r & 15], sn = rp[16 + (r & 15)];
; #pragma unroll
;                 for (int ni = 0; ni < 4; ++ni) {
;                     const int nb = pn * 256 + wc * 128 + ni * 32, n = nb + r;
;                     float v = acc[mi][ni][reg] * rq;
;                     if (((nb >> 5) % 3) == 2) {
;                         const float o = __builtin_bit_cast(float, __builtin_amdgcn_ds_swizzle(__builtin_bit_cast(int, v), 0x401f));
;                         v = (r < 16) ? (v * cs - o * sn) : (v * cs + o * sn);
.LBB0_286:
	s_lshl_b32 s5, s15, 7
	s_waitcnt vmcnt(9)
	v_lshl_add_u32 v132, v188, 6, s5
	v_lshl_or_b32 v134, v186, 2, v132
	v_ashrrev_i32_e32 v135, 31, v134
	v_lshl_add_u64 v[132:133], v[134:135], 2, s[28:29]
	v_and_b32_e32 v130, 15, v187
	v_mov_b32_e32 v224, v132
	v_mov_b32_e32 v225, v133
	v_add_u32_e32 v132, s13, v134
	v_lshlrev_b32_e32 v130, 2, v130
	v_mov_b32_e32 v131, v1
	v_ashrrev_i32_e32 v133, 31, v132
	v_lshl_add_u64 v[130:131], s[30:31], 0, v[130:131]
	v_lshlrev_b64 v[132:133], 7, v[132:133]
	v_lshl_add_u64 v[132:133], v[130:131], 0, v[132:133]
	v_mov_b32_e32 v226, v132
	v_mov_b32_e32 v227, v133
	v_add_co_u32_e32 v234, vcc, 0x1000, v132
	s_nop 1
	v_addc_co_u32_e32 v235, vcc, 0, v133, vcc
	global_load_dword v192, v[224:225], off
	global_load_dword v193, v[226:227], off
	global_load_dword v194, v[226:227], off offset:64
	global_load_dword v195, v[224:225], off offset:4
	global_load_dword v196, v[226:227], off offset:128
	global_load_dword v197, v[226:227], off offset:192
	global_load_dword v198, v[224:225], off offset:8
	global_load_dword v199, v[226:227], off offset:256
	global_load_dword v200, v[226:227], off offset:320
	global_load_dword v201, v[224:225], off offset:12
	global_load_dword v202, v[226:227], off offset:384
	global_load_dword v203, v[226:227], off offset:448
	global_load_dword v204, v[224:225], off offset:32
	global_load_dword v205, v[226:227], off offset:1024
	global_load_dword v206, v[226:227], off offset:1088
	global_load_dword v207, v[224:225], off offset:36
	global_load_dword v208, v[226:227], off offset:1152
	global_load_dword v209, v[226:227], off offset:1216
	global_load_dword v210, v[224:225], off offset:40
	global_load_dword v211, v[226:227], off offset:1280
	global_load_dword v212, v[226:227], off offset:1344
	global_load_dword v213, v[224:225], off offset:44
	global_load_dword v214, v[226:227], off offset:1408
	global_load_dword v215, v[226:227], off offset:1472
	global_load_dword v216, v[224:225], off offset:64
	global_load_dword v217, v[226:227], off offset:2048
	global_load_dword v218, v[226:227], off offset:2112
	s_lshl_b32 s4, s4, 8
	v_lshl_or_b32 v136, v181, 7, s4
	s_waitcnt vmcnt(34)
	v_ashrrev_i32_e32 v142, 5, v136
	s_mov_b32 s4, 0x55555556
	v_mul_hi_i32 v132, v142, s4
	v_lshrrev_b32_e32 v133, 31, v132
	v_add_u32_e32 v132, v132, v133
	v_lshl_add_u32 v132, v132, 1, v132
	v_sub_u32_e32 v132, v142, v132
	v_cmp_gt_u32_e32 vcc, 16, v0
	v_cmp_eq_u32_e64 s[40:41], 2, v132
	s_waitcnt vmcnt(24)
	v_mul_f32_e32 v114, v114, v192
	s_and_saveexec_b64 s[4:5], s[40:41]
	s_cbranch_execz .LBB0_288
	ds_swizzle_b32 v132, v114 offset:swizzle(SWAP,16)
	s_waitcnt lgkmcnt(0)
	v_mul_f32_e32 v132, v194, v132
	v_cndmask_b32_e64 v132, v132, -v132, vcc
	v_fmac_f32_e32 v132, v193, v114
	v_mov_b32_e32 v114, v132
